# attention unit order: each XCD queue walks one (batch,head) pair completely before the other (was interleaved)
# speedup vs baseline: 1.0070x; 1.0070x over previous
; #define A_FETCH(res) do { res = 0xffffffffu; \
;             for (unsigned i_ = 0; i_ < 8u && res == 0xffffffffu; ++i_) { const unsigned j_ = (xcc + i_) & 7u; \
;                 if (dead & (1u << j_)) continue; \
;                 const unsigned k_ = atomicAdd(a.ctr + 32 * j_, 1u); \
;                 if (k_ < 2u * NQB) res = (j_ << 8) | k_; else dead |= 1u << j_; } } while (0)
; __device__ __forceinline__ void attn_phase(LAS unsigned char* lds, const AttnArgs& a, int tid_in) {
;     ...
;         if (tid == 0) { unsigned res; A_FETCH(res); *sU = res; }
;         __syncthreads();
;         const unsigned u0 = *sU;
;         __syncthreads();
;         if (u0 == 0xffffffffu) return;
;         A_UNIT_PRELOAD(u0, qb, b, h, NT, rowb);
.LBB0_568:
	s_or_b64 exec, exec, s[10:11]
	v_readlane_b32 s3, v255, 0
	s_waitcnt lgkmcnt(0)
	s_barrier
	v_mov_b32_e32 v0, s3
	ds_read_b32 v0, v0
	s_waitcnt lgkmcnt(0)
	s_barrier
	v_cmp_eq_u32_e32 vcc, -1, v0
	v_readfirstlane_b32 s6, v0
	v_cmp_ne_u32_e64 s[38:39], -1, v0
	s_cbranch_vccnz .LBB0_570
	s_and_b32 s20, s6, 0xff
	s_cmp_gt_u32 s20, 64
	s_cselect_b32 s11, 1, 0
	s_cselect_b32 s10, 0x41, 0
	s_sub_i32 s20, s20, s10
	s_lshr_b32 s10, s6, 7
	v_mov_b32_e32 v6, v193
	s_sub_i32 s3, 64, s20
	s_and_b32 s10, s10, 2
	s_movk_i32 s14, 0x60
	v_lshrrev_b32_e32 v0, 1, v6
	v_and_b32_e32 v7, 31, v6
	s_or_b32 s33, s10, s11
	s_lshr_b32 s6, s6, 9
	s_lshl_b32 s10, s3, 1
	v_and_or_b32 v0, v0, s14, v7
	s_lshl_b32 s14, s3, 7
	s_add_i32 s21, s10, 2
	s_mul_i32 s10, s6, 0x2010
	s_ashr_i32 s15, s14, 31
	s_mul_hi_u32 s11, s6, 0x2010
	s_add_u32 s14, s10, s14
	s_addc_u32 s15, s11, s15
	s_mulk_i32 s15, 0x1400
	s_mul_hi_u32 s27, s14, 0x1400
	s_add_i32 s27, s27, s15
	s_mulk_i32 s14, 0x1400
	v_ashrrev_i32_e32 v7, 2, v6
	s_add_u32 s14, s16, s14
	v_and_b32_e32 v7, 0xffffffc0, v7
	s_movk_i32 s31, 0xa00
	s_addc_u32 s15, s17, s27
	s_lshl_b32 s27, s33, 8
	v_mad_u32_u24 v0, v0, s31, v7
	v_lshrrev_b32_e32 v7, 2, v6
	s_add_u32 s14, s14, s27
	v_and_or_b32 v0, v7, 8, v0
	v_lshrrev_b32_e32 v8, 4, v6
	s_addc_u32 s15, s15, 0
	v_lshlrev_b32_e32 v9, 3, v6
	v_lshl_add_u64 v[6:7], v[0:1], 1, s[14:15]
	v_mul_lo_u32 v0, v8, s31
	s_movk_i32 s14, 0x78
	v_and_or_b32 v0, v9, s14, v0
	s_mul_hi_u32 s14, s6, 0x2814000
	s_mul_i32 s6, s6, 0x2814000
	s_add_u32 s6, s16, s6
	s_addc_u32 s15, s17, s14
	s_add_u32 s14, s6, s27
	s_addc_u32 s15, s15, 0
	global_load_dwordx4 v[144:147], v[6:7], off
	global_load_dwordx4 v[148:151], v[6:7], off offset:32
	global_load_dwordx4 v[152:155], v[6:7], off offset:64
	global_load_dwordx4 v[156:159], v[6:7], off offset:96
	v_lshl_add_u64 v[6:7], v[0:1], 1, s[14:15]
	v_add_co_u32_e32 v8, vcc, 0x28000, v6
	global_load_dwordx4 v[160:163], v[6:7], off offset:1024
	global_load_dwordx4 v[164:167], v[6:7], off offset:2048
	v_addc_co_u32_e32 v9, vcc, 0, v7, vcc
	global_load_dwordx4 v[168:171], v[8:9], off offset:1024
	global_load_dwordx4 v[172:175], v[8:9], off offset:2048
	s_mov_b64 s[14:15], 0x400
	s_cmp_lg_u32 s20, 0
	v_lshl_add_u64 v[202:203], v[6:7], 0, s[14:15]
	s_cselect_b32 s27, s21, 0x81

; __device__ __forceinline__ void attn_phase(LAS unsigned char* lds, const AttnArgs& a, int tid_in) {
;     ...
;         const unsigned un = *sU;
;         int nqb = 0, nb = 0, nh = 0, nNT = 0; size_t nrowb = 0;
;         if (un != 0xffffffffu) A_UNIT_PRELOAD(un, nqb, nb, nh, nNT, nrowb);
.LBB0_604:
	v_readlane_b32 s4, v255, 0
	s_waitcnt lgkmcnt(0)
	s_barrier
	v_mov_b32_e32 v0, s4
	ds_read_b32 v0, v0
	s_waitcnt lgkmcnt(0)
	v_cmp_eq_u32_e64 s[40:41], -1, v0
	v_readfirstlane_b32 s4, v0
	s_and_b64 vcc, exec, s[40:41]
	s_cbranch_vccnz .LBB0_606
	s_and_b32 s27, s4, 0xff
	s_cmp_gt_u32 s27, 64
	s_cselect_b32 s30, 1, 0
	s_cselect_b32 s5, 0x41, 0
	s_sub_i32 s27, s27, s5
	s_lshr_b32 s5, s4, 7
	s_and_b32 s5, s5, 2
	v_mov_b32_e32 v98, v193
	s_sub_i32 s6, 64, s27
	s_or_b32 s34, s5, s30
	s_movk_i32 s30, 0x60
	v_lshrrev_b32_e32 v0, 1, v98
	v_and_b32_e32 v99, 31, v98
	s_lshr_b32 s35, s4, 9
	s_lshl_b32 s4, s6, 1
	v_and_or_b32 v0, v0, s30, v99
	s_lshl_b32 s30, s6, 7
	s_add_i32 s42, s4, 2
	s_mul_i32 s4, s35, 0x2010
	s_ashr_i32 s31, s30, 31
	s_mul_hi_u32 s5, s35, 0x2010
	s_add_u32 s30, s4, s30
	s_addc_u32 s31, s5, s31
	s_mulk_i32 s31, 0x1400
	s_mul_hi_u32 s43, s30, 0x1400
	s_add_i32 s43, s43, s31
	s_mulk_i32 s30, 0x1400
	v_ashrrev_i32_e32 v99, 2, v98
	s_add_u32 s30, s16, s30
	v_and_b32_e32 v99, 0xffffffc0, v99
	s_movk_i32 s44, 0xa00
	s_addc_u32 s31, s17, s43
	s_lshl_b32 s43, s34, 8
	v_mad_u32_u24 v0, v0, s44, v99
	v_lshrrev_b32_e32 v99, 2, v98
	s_add_u32 s30, s30, s43
	v_and_or_b32 v0, v99, 8, v0
	v_lshrrev_b32_e32 v100, 4, v98
	s_addc_u32 s31, s31, 0
	v_lshlrev_b32_e32 v101, 3, v98
	v_lshl_add_u64 v[98:99], v[0:1], 1, s[30:31]
	v_mul_lo_u32 v0, v100, s44
	s_movk_i32 s30, 0x78
	v_and_or_b32 v0, v101, s30, v0
	s_mul_hi_u32 s30, s35, 0x2814000
	s_mul_i32 s35, s35, 0x2814000
	s_add_u32 s31, s16, s35
	s_addc_u32 s35, s17, s30
	s_add_u32 s30, s31, s43
	s_addc_u32 s31, s35, 0
	global_load_dwordx4 v[144:147], v[98:99], off
	global_load_dwordx4 v[148:151], v[98:99], off offset:32
	global_load_dwordx4 v[152:155], v[98:99], off offset:64
	global_load_dwordx4 v[156:159], v[98:99], off offset:96
	v_lshl_add_u64 v[98:99], v[0:1], 1, s[30:31]
	v_add_co_u32_e32 v100, vcc, 0x28000, v98
	global_load_dwordx4 v[160:163], v[98:99], off offset:1024
	global_load_dwordx4 v[164:167], v[98:99], off offset:2048
	v_addc_co_u32_e32 v101, vcc, 0, v99, vcc
	global_load_dwordx4 v[168:171], v[100:101], off offset:1024
	global_load_dwordx4 v[172:175], v[100:101], off offset:2048
	s_mov_b64 s[30:31], 0x400
	s_cmp_lg_u32 s27, 0
	v_lshl_add_u64 v[202:203], v[98:99], 0, s[30:31]
	s_cselect_b32 s27, s42, 0x81
	s_andn2_b64 vcc, exec, s[20:21]
	s_cbranch_vccz .LBB0_607
	s_branch .LBB0_608
